# kernel-start cooperative sync: only workgroup 0 (which zeroed the control words) does the L2 writeback; its stores are drained before its barrier; on top of all30
# speedup vs baseline: 1.0025x; 1.0025x over previous
; #define GAS __attribute__((address_space(1)))
; __global__ void __launch_bounds__(NWAVES * 64, 2) hybrid_fwd(const Args A) {
;     ...
;     if (hi - lo > 1) {
;         if (blockIdx.x == 0) { GAS v4u* z = (GAS v4u*)(F.ws + WS_CTL); for (int i = F.tid; i < (int)(CTL_ZERO_BYTES / 16); i += NWAVES * 64) if (i < (int)(WS_PRM / 16) || i >= (int)((CW_SEAM * 4) / 16)) z[i] = (v4u){0u, 0u, 0u, 0u}; }
;         grid.sync();
.LBB0_10:
	s_or_b64 exec, exec, s[4:5]
	v_lshrrev_b32_e32 v2, 20, v0
	v_lshrrev_b32_e32 v0, 10, v0
	v_or_b32_e32 v0, v0, v2
	s_movk_i32 s4, 0x3ff
	v_and_or_b32 v0, v0, s4, v1
	v_cmp_eq_u32_e32 vcc, 0, v0
	s_waitcnt vmcnt(0)
	s_barrier
	s_and_saveexec_b64 s[4:5], vcc
	s_cbranch_execz .LBB0_20
	s_cmp_lg_u32 s82, 0
	s_cbranch_scc1 .Lcg_nowb
	buffer_wbl2 sc1
.Lcg_nowb:
	s_waitcnt vmcnt(0)
	s_load_dwordx2 s[2:3], s[2:3], 0x58
	v_mov_b32_e32 v2, 0
	s_mov_b64 s[6:7], exec
	v_mbcnt_lo_u32_b32 v1, s6, 0
	v_mbcnt_hi_u32_b32 v1, s7, v1
	s_waitcnt lgkmcnt(0)
	global_load_dword v0, v2, s[2:3] offset:40
	v_cmp_eq_u32_e32 vcc, 0, v1
	s_and_saveexec_b64 s[8:9], vcc
	s_cbranch_execz .LBB0_13
	s_bcnt1_i32_b64 s6, s[6:7]
	v_mov_b32_e32 v3, s6
	global_atomic_add v3, v2, v3, s[2:3] offset:32 sc0
